# in-proj K rotation keyed on CU group: first slice = 2*((CU>>2)&7)
# baseline (speedup 1.0000x reference)
; DI int tidx() { int t = threadIdx.x; asm volatile("" : "+v"(t)); return t; }
; template <int EPI>
; DI void gemm_phase(const P& p, int l, const u16* __restrict__ A, const u16* __restrict__ Bt, int mpx, char* lds) {
;   const int tid = tidx();
;   int t = 0;
;   int m0, n0;
;   if (!tile_coords<EPI>(t, mpx, m0, n0)) return;
;   const unsigned voffb = (unsigned)(((tid >> 3) * 1024 + (tid & 7) * 8) * 2);
;   const u16* Ag = A + (size_t)m0 * 1024;
;   const u16* Bg = Bt + (size_t)n0 * 1024;
;   uint4 ra0, ra1, ra2, ra3, rb0, rb1, rb2, rb3;
;     ...
;   GLOAD(Ag, Bg, 0)
;   u16* As0 = (u16*)lds;
;   u16* Bs0 = As0 + 256 * 64;
;   u16* As1 = Bs0 + 256 * 64;
;   u16* Bs1 = As1 + 256 * 64;
;   const int lw = (tid >> 3) * 64 + (((tid & 7) ^ ((tid >> 3) & 7)) * 8);
;   GSTORE(As0, Bs0)
.LBB0_81:
	s_mov_b32 s57, s3
	s_lshl_b64 s[42:43], s[56:57], 11
	s_lshl_b32 s2, s51, 11
	s_add_u32 s58, s16, s42
	s_addc_u32 s59, s17, s43
	s_add_u32 s60, s24, s2
	s_addc_u32 s61, s25, 0
	v_lshrrev_b32_e32 v166, 3, v195
	v_and_b32_e32 v167, 7, v195
	v_and_b32_e32 v168, 7, v166
	v_xor_b32_e32 v167, v167, v168
	v_lshlrev_b32_e32 v167, 4, v167
	v_lshl_or_b32 v162, v166, 11, v167
	v_add_u32_e32 v163, s33, v162
	v_add_u32_e32 v164, s35, v162
	v_add_u32_e32 v165, s39, v162
	v_readfirstlane_b32 s47, v195
	s_lshr_b32 s47, s47, 6
	s_lshl_b32 s47, s47, 10
	s_bfe_u32 s48, s84, 0x30002
	s_lshl_b32 s48, s48, 1
	s_mov_b32 s49, 0
	s_waitcnt lgkmcnt(0)
	s_barrier
	s_cmp_eq_u32 s101, 0
	s_cbranch_scc1 .Lrot_in_nofirst
	s_mov_b32 s101, 0
	s_lshl_b32 s2, s48, 7
	s_add_u32 s44, s40, s2
	s_addc_u32 s45, s41, 0
	s_add_u32 s42, s0, s2
	s_addc_u32 s43, s1, 0
	s_add_i32 m0, s47, 0x20
	s_nop 0
	global_load_lds_dwordx4 v162, s[44:45]
	s_add_i32 m0, s47, 0x2020
	s_nop 0
	global_load_lds_dwordx4 v163, s[44:45]
	s_add_i32 m0, s47, 0x4020
	s_nop 0
	global_load_lds_dwordx4 v164, s[44:45]
	s_add_i32 m0, s47, 0x6020
	s_nop 0
	global_load_lds_dwordx4 v165, s[44:45]
	s_add_i32 m0, s47, 0x8020
	s_nop 0
	global_load_lds_dwordx4 v162, s[42:43]
	s_add_i32 m0, s47, 0xa020
	s_nop 0
	global_load_lds_dwordx4 v163, s[42:43]
	s_add_i32 m0, s47, 0xc020
	s_nop 0
	global_load_lds_dwordx4 v164, s[42:43]
	s_add_i32 m0, s47, 0xe020
	s_nop 0
	global_load_lds_dwordx4 v165, s[42:43]
	s_waitcnt vmcnt(0)
	s_barrier

; #define GCOMPUTE(AS, BS) GCOMPUTE_KS(AS, BS, 0) GCOMPUTE_KS(AS, BS, 1)
; template <int EPI>
; DI void gemm_phase(const P& p, int l, const u16* __restrict__ A, const u16* __restrict__ Bt, int mpx, char* lds) {
;     ...
;   for (int kk = 1; kk < 15; kk += 2) {
;     __syncthreads();
;     GSTORE(As0, Bs0)
;     GLOAD(Ag, Bg, (kk + 2) * 64)
;     __builtin_amdgcn_sched_barrier(0);
;     GCOMPUTE(As1, Bs1)
;     __builtin_amdgcn_sched_barrier(0);
;     __syncthreads();
;     GSTORE(As1, Bs1)
;     {
;       const bool in_tile = kk + 3 < 16;
;       const u16* pa = in_tile ? Ag : Agn;
;       const u16* pb = in_tile ? Bg : Bgn;
;       const int k0 = in_tile ? (kk + 3) * 64 : 0;
;       GLOAD(pa, pb, k0)
;     }
;     __builtin_amdgcn_sched_barrier(0);
;     GCOMPUTE(As0, Bs0)
;     __builtin_amdgcn_sched_barrier(0);
.LBB0_82:
	s_waitcnt lgkmcnt(3)
	v_mfma_f32_16x16x32_bf16 v[6:9], v[238:241], v[212:215], v[6:9]
	v_mfma_f32_16x16x32_bf16 v[10:13], v[238:241], v[216:219], v[10:13]
	v_mfma_f32_16x16x32_bf16 v[14:17], v[238:241], v[220:223], v[14:17]
	v_mfma_f32_16x16x32_bf16 v[18:21], v[238:241], v[234:237], v[18:21]
	ds_read_b128 v[238:241], v199 offset:8192
	s_add_i32 m0, s47, 0x20
	s_nop 0
	global_load_lds_dwordx4 v162, s[44:45]
	s_add_i32 m0, s47, 0x2020
	s_nop 0
	global_load_lds_dwordx4 v163, s[44:45]
	s_waitcnt lgkmcnt(3)
	v_mfma_f32_16x16x32_bf16 v[22:25], v[242:245], v[212:215], v[22:25]
	v_mfma_f32_16x16x32_bf16 v[26:29], v[242:245], v[216:219], v[26:29]
	v_mfma_f32_16x16x32_bf16 v[30:33], v[242:245], v[220:223], v[30:33]
	v_mfma_f32_16x16x32_bf16 v[34:37], v[242:245], v[234:237], v[34:37]
	ds_read_b128 v[242:245], v199 offset:10240
	ds_read_b128 v[130:133], v200
	s_add_i32 m0, s47, 0x4020
	s_nop 0
	global_load_lds_dwordx4 v164, s[44:45]
	s_add_i32 m0, s47, 0x6020
	s_nop 0
	global_load_lds_dwordx4 v165, s[44:45]
	s_waitcnt lgkmcnt(4)
	v_mfma_f32_16x16x32_bf16 v[38:41], v[246:249], v[212:215], v[38:41]
	v_mfma_f32_16x16x32_bf16 v[42:45], v[246:249], v[216:219], v[42:45]
	v_mfma_f32_16x16x32_bf16 v[46:49], v[246:249], v[220:223], v[46:49]
	v_mfma_f32_16x16x32_bf16 v[50:53], v[246:249], v[234:237], v[50:53]
	ds_read_b128 v[246:249], v199 offset:12288
	ds_read_b128 v[134:137], v200 offset:2048
	s_add_i32 m0, s47, 0x8020
	s_nop 0
	global_load_lds_dwordx4 v162, s[42:43]
	s_add_i32 m0, s47, 0xa020
	s_nop 0
	global_load_lds_dwordx4 v163, s[42:43]
	s_waitcnt lgkmcnt(5)
	v_mfma_f32_16x16x32_bf16 v[54:57], v[250:253], v[212:215], v[54:57]
	v_mfma_f32_16x16x32_bf16 v[58:61], v[250:253], v[216:219], v[58:61]
	v_mfma_f32_16x16x32_bf16 v[62:65], v[250:253], v[220:223], v[62:65]
	v_mfma_f32_16x16x32_bf16 v[66:69], v[250:253], v[234:237], v[66:69]
	ds_read_b128 v[250:253], v199 offset:14336
	ds_read_b128 v[138:141], v200 offset:4096
	s_add_i32 m0, s47, 0xc020
	s_nop 0
	global_load_lds_dwordx4 v164, s[42:43]
	s_add_i32 m0, s47, 0xe020
	s_nop 0
	global_load_lds_dwordx4 v165, s[42:43]
	s_waitcnt lgkmcnt(6)
	v_mfma_f32_16x16x32_bf16 v[70:73], v[238:241], v[212:215], v[70:73]
	v_mfma_f32_16x16x32_bf16 v[74:77], v[238:241], v[216:219], v[74:77]
	v_mfma_f32_16x16x32_bf16 v[78:81], v[238:241], v[220:223], v[78:81]
	v_mfma_f32_16x16x32_bf16 v[82:85], v[238:241], v[234:237], v[82:85]
	ds_read_b128 v[238:241], v233
	ds_read_b128 v[142:145], v200 offset:6144
	s_waitcnt lgkmcnt(7)
	v_mfma_f32_16x16x32_bf16 v[86:89], v[242:245], v[212:215], v[86:89]
	v_mfma_f32_16x16x32_bf16 v[90:93], v[242:245], v[216:219], v[90:93]
	v_mfma_f32_16x16x32_bf16 v[94:97], v[242:245], v[220:223], v[94:97]
	v_mfma_f32_16x16x32_bf16 v[98:101], v[242:245], v[234:237], v[98:101]
	ds_read_b128 v[242:245], v233 offset:2048
	s_waitcnt lgkmcnt(6)
	v_mfma_f32_16x16x32_bf16 v[102:105], v[246:249], v[212:215], v[102:105]
	v_mfma_f32_16x16x32_bf16 v[106:109], v[246:249], v[216:219], v[106:109]
	v_mfma_f32_16x16x32_bf16 v[110:113], v[246:249], v[220:223], v[110:113]
	v_mfma_f32_16x16x32_bf16 v[114:117], v[246:249], v[234:237], v[114:117]
	ds_read_b128 v[246:249], v233 offset:4096
	s_waitcnt lgkmcnt(5)
	v_mfma_f32_16x16x32_bf16 v[118:121], v[250:253], v[212:215], v[118:121]
	v_mfma_f32_16x16x32_bf16 v[122:125], v[250:253], v[216:219], v[122:125]
	v_mfma_f32_16x16x32_bf16 v[126:129], v[250:253], v[220:223], v[126:129]
	v_mfma_f32_16x16x32_bf16 v[2:5], v[250:253], v[234:237], v[2:5]
	ds_read_b128 v[250:253], v233 offset:6144
	s_waitcnt lgkmcnt(3)
	v_mfma_f32_16x16x32_bf16 v[6:9], v[238:241], v[130:133], v[6:9]
	v_mfma_f32_16x16x32_bf16 v[10:13], v[238:241], v[134:137], v[10:13]
	v_mfma_f32_16x16x32_bf16 v[14:17], v[238:241], v[138:141], v[14:17]
	v_mfma_f32_16x16x32_bf16 v[18:21], v[238:241], v[142:145], v[18:21]
	ds_read_b128 v[238:241], v233 offset:8192
	s_waitcnt lgkmcnt(3)
	v_mfma_f32_16x16x32_bf16 v[22:25], v[242:245], v[130:133], v[22:25]
	v_mfma_f32_16x16x32_bf16 v[26:29], v[242:245], v[134:137], v[26:29]
	v_mfma_f32_16x16x32_bf16 v[30:33], v[242:245], v[138:141], v[30:33]
	v_mfma_f32_16x16x32_bf16 v[34:37], v[242:245], v[142:145], v[34:37]
	ds_read_b128 v[242:245], v233 offset:10240
	s_waitcnt lgkmcnt(3)
	v_mfma_f32_16x16x32_bf16 v[38:41], v[246:249], v[130:133], v[38:41]
	v_mfma_f32_16x16x32_bf16 v[42:45], v[246:249], v[134:137], v[42:45]
	v_mfma_f32_16x16x32_bf16 v[46:49], v[246:249], v[138:141], v[46:49]
	v_mfma_f32_16x16x32_bf16 v[50:53], v[246:249], v[142:145], v[50:53]
	ds_read_b128 v[246:249], v233 offset:12288
	s_waitcnt lgkmcnt(3)
	v_mfma_f32_16x16x32_bf16 v[54:57], v[250:253], v[130:133], v[54:57]
	v_mfma_f32_16x16x32_bf16 v[58:61], v[250:253], v[134:137], v[58:61]
	v_mfma_f32_16x16x32_bf16 v[62:65], v[250:253], v[138:141], v[62:65]
	v_mfma_f32_16x16x32_bf16 v[66:69], v[250:253], v[142:145], v[66:69]
	ds_read_b128 v[250:253], v233 offset:14336
	s_waitcnt lgkmcnt(3)
	v_mfma_f32_16x16x32_bf16 v[70:73], v[238:241], v[130:133], v[70:73]
	v_mfma_f32_16x16x32_bf16 v[74:77], v[238:241], v[134:137], v[74:77]
	v_mfma_f32_16x16x32_bf16 v[78:81], v[238:241], v[138:141], v[78:81]
	v_mfma_f32_16x16x32_bf16 v[82:85], v[238:241], v[142:145], v[82:85]
	s_waitcnt lgkmcnt(2)
	v_mfma_f32_16x16x32_bf16 v[86:89], v[242:245], v[130:133], v[86:89]
	v_mfma_f32_16x16x32_bf16 v[90:93], v[242:245], v[134:137], v[90:93]
	v_mfma_f32_16x16x32_bf16 v[94:97], v[242:245], v[138:141], v[94:97]
	v_mfma_f32_16x16x32_bf16 v[98:101], v[242:245], v[142:145], v[98:101]
	s_waitcnt lgkmcnt(0)
	s_waitcnt vmcnt(0)
	s_add_i32 s48, s48, 1
	s_and_b32 s48, s48, 15
	s_lshl_b32 s2, s48, 7
	s_add_u32 s44, s40, s2
	s_addc_u32 s45, s41, 0
	s_add_u32 s42, s0, s2
	s_addc_u32 s43, s1, 0
	s_barrier
; #define GCOMPUTE(AS, BS) GCOMPUTE_KS(AS, BS, 0) GCOMPUTE_KS(AS, BS, 1)
; template <int EPI>
; DI void gemm_phase(const P& p, int l, const u16* __restrict__ A, const u16* __restrict__ Bt, int mpx, char* lds) {
;     ...
;   for (int kk = 1; kk < 15; kk += 2) {
;     __syncthreads();
;     GSTORE(As0, Bs0)
;     GLOAD(Ag, Bg, (kk + 2) * 64)
;     __builtin_amdgcn_sched_barrier(0);
;     GCOMPUTE(As1, Bs1)
;     __builtin_amdgcn_sched_barrier(0);
;     __syncthreads();
;     GSTORE(As1, Bs1)
;     {
;       const bool in_tile = kk + 3 < 16;
;       const u16* pa = in_tile ? Ag : Agn;
;       const u16* pb = in_tile ? Bg : Bgn;
;       const int k0 = in_tile ? (kk + 3) * 64 : 0;
;       GLOAD(pa, pb, k0)
;     }
;     __builtin_amdgcn_sched_barrier(0);
;     GCOMPUTE(As0, Bs0)
;     __builtin_amdgcn_sched_barrier(0);
	ds_read_b128 v[212:215], v204 offset:32768
	ds_read_b128 v[216:219], v204 offset:34816
	ds_read_b128 v[220:223], v204 offset:36864
	ds_read_b128 v[234:237], v204 offset:38912
	ds_read_b128 v[238:241], v205
	ds_read_b128 v[242:245], v205 offset:2048
	v_mfma_f32_16x16x32_bf16 v[102:105], v[246:249], v[130:133], v[102:105]
	v_mfma_f32_16x16x32_bf16 v[106:109], v[246:249], v[134:137], v[106:109]
	v_mfma_f32_16x16x32_bf16 v[110:113], v[246:249], v[138:141], v[110:113]
	v_mfma_f32_16x16x32_bf16 v[114:117], v[246:249], v[142:145], v[114:117]
	ds_read_b128 v[246:249], v205 offset:4096
	v_mfma_f32_16x16x32_bf16 v[118:121], v[250:253], v[130:133], v[118:121]
	v_mfma_f32_16x16x32_bf16 v[122:125], v[250:253], v[134:137], v[122:125]
	v_mfma_f32_16x16x32_bf16 v[126:129], v[250:253], v[138:141], v[126:129]
	v_mfma_f32_16x16x32_bf16 v[2:5], v[250:253], v[142:145], v[2:5]
	ds_read_b128 v[250:253], v205 offset:6144
	s_waitcnt lgkmcnt(3)
	v_mfma_f32_16x16x32_bf16 v[6:9], v[238:241], v[212:215], v[6:9]
	v_mfma_f32_16x16x32_bf16 v[10:13], v[238:241], v[216:219], v[10:13]
	v_mfma_f32_16x16x32_bf16 v[14:17], v[238:241], v[220:223], v[14:17]
	v_mfma_f32_16x16x32_bf16 v[18:21], v[238:241], v[234:237], v[18:21]
	ds_read_b128 v[238:241], v205 offset:8192
	s_add_i32 m0, s47, 0x10020
	s_nop 0
	global_load_lds_dwordx4 v162, s[44:45]
	s_add_i32 m0, s47, 0x12020
	s_nop 0
	global_load_lds_dwordx4 v163, s[44:45]
	s_waitcnt lgkmcnt(3)
	v_mfma_f32_16x16x32_bf16 v[22:25], v[242:245], v[212:215], v[22:25]
	v_mfma_f32_16x16x32_bf16 v[26:29], v[242:245], v[216:219], v[26:29]
	v_mfma_f32_16x16x32_bf16 v[30:33], v[242:245], v[220:223], v[30:33]
	v_mfma_f32_16x16x32_bf16 v[34:37], v[242:245], v[234:237], v[34:37]
	ds_read_b128 v[242:245], v205 offset:10240
	ds_read_b128 v[130:133], v206 offset:32768
	s_add_i32 m0, s47, 0x14020
	s_nop 0
	global_load_lds_dwordx4 v164, s[44:45]
	s_add_i32 m0, s47, 0x16020
	s_nop 0
	global_load_lds_dwordx4 v165, s[44:45]
	s_waitcnt lgkmcnt(4)
	v_mfma_f32_16x16x32_bf16 v[38:41], v[246:249], v[212:215], v[38:41]
	v_mfma_f32_16x16x32_bf16 v[42:45], v[246:249], v[216:219], v[42:45]
	v_mfma_f32_16x16x32_bf16 v[46:49], v[246:249], v[220:223], v[46:49]
	v_mfma_f32_16x16x32_bf16 v[50:53], v[246:249], v[234:237], v[50:53]
	ds_read_b128 v[246:249], v205 offset:12288
	ds_read_b128 v[134:137], v206 offset:34816
	s_add_i32 m0, s47, 0x18020
	s_nop 0
	global_load_lds_dwordx4 v162, s[42:43]
	s_add_i32 m0, s47, 0x1a020
	s_nop 0
	global_load_lds_dwordx4 v163, s[42:43]
	s_waitcnt lgkmcnt(5)
	v_mfma_f32_16x16x32_bf16 v[54:57], v[250:253], v[212:215], v[54:57]
	v_mfma_f32_16x16x32_bf16 v[58:61], v[250:253], v[216:219], v[58:61]
	v_mfma_f32_16x16x32_bf16 v[62:65], v[250:253], v[220:223], v[62:65]
	v_mfma_f32_16x16x32_bf16 v[66:69], v[250:253], v[234:237], v[66:69]
	ds_read_b128 v[250:253], v205 offset:14336
	ds_read_b128 v[138:141], v206 offset:36864
	s_add_i32 m0, s47, 0x1c020
	s_nop 0
	global_load_lds_dwordx4 v164, s[42:43]
	s_add_i32 m0, s47, 0x1e020
	s_nop 0
	global_load_lds_dwordx4 v165, s[42:43]
	s_waitcnt lgkmcnt(6)
	v_mfma_f32_16x16x32_bf16 v[70:73], v[238:241], v[212:215], v[70:73]
	v_mfma_f32_16x16x32_bf16 v[74:77], v[238:241], v[216:219], v[74:77]
	v_mfma_f32_16x16x32_bf16 v[78:81], v[238:241], v[220:223], v[78:81]
	v_mfma_f32_16x16x32_bf16 v[82:85], v[238:241], v[234:237], v[82:85]
	ds_read_b128 v[238:241], v207
	ds_read_b128 v[142:145], v206 offset:38912
	s_waitcnt lgkmcnt(7)
	v_mfma_f32_16x16x32_bf16 v[86:89], v[242:245], v[212:215], v[86:89]
	v_mfma_f32_16x16x32_bf16 v[90:93], v[242:245], v[216:219], v[90:93]
	v_mfma_f32_16x16x32_bf16 v[94:97], v[242:245], v[220:223], v[94:97]
	v_mfma_f32_16x16x32_bf16 v[98:101], v[242:245], v[234:237], v[98:101]
	ds_read_b128 v[242:245], v207 offset:2048
	s_waitcnt lgkmcnt(6)
	v_mfma_f32_16x16x32_bf16 v[102:105], v[246:249], v[212:215], v[102:105]
	v_mfma_f32_16x16x32_bf16 v[106:109], v[246:249], v[216:219], v[106:109]
	v_mfma_f32_16x16x32_bf16 v[110:113], v[246:249], v[220:223], v[110:113]
	v_mfma_f32_16x16x32_bf16 v[114:117], v[246:249], v[234:237], v[114:117]
	ds_read_b128 v[246:249], v207 offset:4096
	s_waitcnt lgkmcnt(5)
	v_mfma_f32_16x16x32_bf16 v[118:121], v[250:253], v[212:215], v[118:121]
	v_mfma_f32_16x16x32_bf16 v[122:125], v[250:253], v[216:219], v[122:125]
	v_mfma_f32_16x16x32_bf16 v[126:129], v[250:253], v[220:223], v[126:129]
	v_mfma_f32_16x16x32_bf16 v[2:5], v[250:253], v[234:237], v[2:5]
	ds_read_b128 v[250:253], v207 offset:6144
	s_waitcnt lgkmcnt(3)
	v_mfma_f32_16x16x32_bf16 v[6:9], v[238:241], v[130:133], v[6:9]
	v_mfma_f32_16x16x32_bf16 v[10:13], v[238:241], v[134:137], v[10:13]
	v_mfma_f32_16x16x32_bf16 v[14:17], v[238:241], v[138:141], v[14:17]
	v_mfma_f32_16x16x32_bf16 v[18:21], v[238:241], v[142:145], v[18:21]
	ds_read_b128 v[238:241], v207 offset:8192
	s_waitcnt lgkmcnt(3)
	v_mfma_f32_16x16x32_bf16 v[22:25], v[242:245], v[130:133], v[22:25]
	v_mfma_f32_16x16x32_bf16 v[26:29], v[242:245], v[134:137], v[26:29]
	v_mfma_f32_16x16x32_bf16 v[30:33], v[242:245], v[138:141], v[30:33]
	v_mfma_f32_16x16x32_bf16 v[34:37], v[242:245], v[142:145], v[34:37]
	ds_read_b128 v[242:245], v207 offset:10240
	s_waitcnt lgkmcnt(3)
	v_mfma_f32_16x16x32_bf16 v[38:41], v[246:249], v[130:133], v[38:41]
	v_mfma_f32_16x16x32_bf16 v[42:45], v[246:249], v[134:137], v[42:45]
	v_mfma_f32_16x16x32_bf16 v[46:49], v[246:249], v[138:141], v[46:49]
	v_mfma_f32_16x16x32_bf16 v[50:53], v[246:249], v[142:145], v[50:53]
	ds_read_b128 v[246:249], v207 offset:12288
	s_waitcnt lgkmcnt(3)
	v_mfma_f32_16x16x32_bf16 v[54:57], v[250:253], v[130:133], v[54:57]
	v_mfma_f32_16x16x32_bf16 v[58:61], v[250:253], v[134:137], v[58:61]
	v_mfma_f32_16x16x32_bf16 v[62:65], v[250:253], v[138:141], v[62:65]
	v_mfma_f32_16x16x32_bf16 v[66:69], v[250:253], v[142:145], v[66:69]
	ds_read_b128 v[250:253], v207 offset:14336
	s_waitcnt lgkmcnt(3)
	v_mfma_f32_16x16x32_bf16 v[70:73], v[238:241], v[130:133], v[70:73]
	v_mfma_f32_16x16x32_bf16 v[74:77], v[238:241], v[134:137], v[74:77]
	v_mfma_f32_16x16x32_bf16 v[78:81], v[238:241], v[138:141], v[78:81]
	v_mfma_f32_16x16x32_bf16 v[82:85], v[238:241], v[142:145], v[82:85]
	s_waitcnt lgkmcnt(2)
	v_mfma_f32_16x16x32_bf16 v[86:89], v[242:245], v[130:133], v[86:89]
	v_mfma_f32_16x16x32_bf16 v[90:93], v[242:245], v[134:137], v[90:93]
	v_mfma_f32_16x16x32_bf16 v[94:97], v[242:245], v[138:141], v[94:97]
	v_mfma_f32_16x16x32_bf16 v[98:101], v[242:245], v[142:145], v[98:101]
	s_waitcnt lgkmcnt(0)
	s_waitcnt vmcnt(0)
	s_add_i32 s48, s48, 1
	s_and_b32 s48, s48, 15
	s_lshl_b32 s2, s48, 7
	s_add_u32 s44, s40, s2
	s_addc_u32 s45, s41, 0
	s_add_u32 s42, s0, s2
	s_addc_u32 s43, s1, 0
	s_add_i32 s49, s49, 1
	s_cmp_lt_u32 s49, 7
	s_barrier
; #define GCOMPUTE(AS, BS) GCOMPUTE_KS(AS, BS, 0) GCOMPUTE_KS(AS, BS, 1)
; template <int EPI>
; DI void gemm_phase(const P& p, int l, const u16* __restrict__ A, const u16* __restrict__ Bt, int mpx, char* lds) {
;     ...
;     __syncthreads();
;     GSTORE(As1, Bs1)
;     {
;       const bool in_tile = kk + 3 < 16;
;       const u16* pa = in_tile ? Ag : Agn;
;       const u16* pb = in_tile ? Bg : Bgn;
;       const int k0 = in_tile ? (kk + 3) * 64 : 0;
;       GLOAD(pa, pb, k0)
;     }
;     __builtin_amdgcn_sched_barrier(0);
;     GCOMPUTE(As0, Bs0)
;     __builtin_amdgcn_sched_barrier(0);
;   }
;   __syncthreads();
;   __builtin_amdgcn_sched_barrier(0);
;   GCOMPUTE(As1, Bs1)
;   __builtin_amdgcn_sched_barrier(0);
	ds_read_b128 v[212:215], v198
	ds_read_b128 v[216:219], v198 offset:2048
	ds_read_b128 v[220:223], v198 offset:4096
	ds_read_b128 v[234:237], v198 offset:6144
	ds_read_b128 v[238:241], v199
	ds_read_b128 v[242:245], v199 offset:2048
	v_mfma_f32_16x16x32_bf16 v[102:105], v[246:249], v[130:133], v[102:105]
	v_mfma_f32_16x16x32_bf16 v[106:109], v[246:249], v[134:137], v[106:109]
	v_mfma_f32_16x16x32_bf16 v[110:113], v[246:249], v[138:141], v[110:113]
	v_mfma_f32_16x16x32_bf16 v[114:117], v[246:249], v[142:145], v[114:117]
	ds_read_b128 v[246:249], v199 offset:4096
	v_mfma_f32_16x16x32_bf16 v[118:121], v[250:253], v[130:133], v[118:121]
	v_mfma_f32_16x16x32_bf16 v[122:125], v[250:253], v[134:137], v[122:125]
	v_mfma_f32_16x16x32_bf16 v[126:129], v[250:253], v[138:141], v[126:129]
	v_mfma_f32_16x16x32_bf16 v[2:5], v[250:253], v[142:145], v[2:5]
	ds_read_b128 v[250:253], v199 offset:6144
	s_cbranch_scc1 .LBB0_82
	s_bfe_u32 s2, s84, 0x30002
	s_lshl_b32 s2, s2, 8
	s_add_u32 s44, s58, s2
	s_addc_u32 s45, s59, 0
	s_add_u32 s42, s60, s2
	s_addc_u32 s43, s61, 0
	s_waitcnt lgkmcnt(3)
	v_mfma_f32_16x16x32_bf16 v[6:9], v[238:241], v[212:215], v[6:9]
	v_mfma_f32_16x16x32_bf16 v[10:13], v[238:241], v[216:219], v[10:13]
	v_mfma_f32_16x16x32_bf16 v[14:17], v[238:241], v[220:223], v[14:17]
	v_mfma_f32_16x16x32_bf16 v[18:21], v[238:241], v[234:237], v[18:21]
	ds_read_b128 v[238:241], v199 offset:8192
	s_add_i32 m0, s47, 0x20
	s_nop 0
	global_load_lds_dwordx4 v162, s[44:45]
	s_add_i32 m0, s47, 0x2020
	s_nop 0
	global_load_lds_dwordx4 v163, s[44:45]
	s_waitcnt lgkmcnt(3)
	v_mfma_f32_16x16x32_bf16 v[22:25], v[242:245], v[212:215], v[22:25]
	v_mfma_f32_16x16x32_bf16 v[26:29], v[242:245], v[216:219], v[26:29]
	v_mfma_f32_16x16x32_bf16 v[30:33], v[242:245], v[220:223], v[30:33]
	v_mfma_f32_16x16x32_bf16 v[34:37], v[242:245], v[234:237], v[34:37]
	ds_read_b128 v[242:245], v199 offset:10240
	ds_read_b128 v[130:133], v200
	s_add_i32 m0, s47, 0x4020
	s_nop 0
	global_load_lds_dwordx4 v164, s[44:45]
	s_add_i32 m0, s47, 0x6020
	s_nop 0
	global_load_lds_dwordx4 v165, s[44:45]
	s_waitcnt lgkmcnt(4)
	v_mfma_f32_16x16x32_bf16 v[38:41], v[246:249], v[212:215], v[38:41]
	v_mfma_f32_16x16x32_bf16 v[42:45], v[246:249], v[216:219], v[42:45]
	v_mfma_f32_16x16x32_bf16 v[46:49], v[246:249], v[220:223], v[46:49]
	v_mfma_f32_16x16x32_bf16 v[50:53], v[246:249], v[234:237], v[50:53]
	ds_read_b128 v[246:249], v199 offset:12288
	ds_read_b128 v[134:137], v200 offset:2048
	s_add_i32 m0, s47, 0x8020
	s_nop 0
	global_load_lds_dwordx4 v162, s[42:43]
	s_add_i32 m0, s47, 0xa020
	s_nop 0
	global_load_lds_dwordx4 v163, s[42:43]
	s_waitcnt lgkmcnt(5)
	v_mfma_f32_16x16x32_bf16 v[54:57], v[250:253], v[212:215], v[54:57]
	v_mfma_f32_16x16x32_bf16 v[58:61], v[250:253], v[216:219], v[58:61]
	v_mfma_f32_16x16x32_bf16 v[62:65], v[250:253], v[220:223], v[62:65]
	v_mfma_f32_16x16x32_bf16 v[66:69], v[250:253], v[234:237], v[66:69]
	ds_read_b128 v[250:253], v199 offset:14336
	ds_read_b128 v[138:141], v200 offset:4096
	s_add_i32 m0, s47, 0xc020
	s_nop 0
	global_load_lds_dwordx4 v164, s[42:43]
	s_add_i32 m0, s47, 0xe020
	s_nop 0
	global_load_lds_dwordx4 v165, s[42:43]
	s_waitcnt lgkmcnt(6)
	v_mfma_f32_16x16x32_bf16 v[70:73], v[238:241], v[212:215], v[70:73]
	v_mfma_f32_16x16x32_bf16 v[74:77], v[238:241], v[216:219], v[74:77]
	v_mfma_f32_16x16x32_bf16 v[78:81], v[238:241], v[220:223], v[78:81]
	v_mfma_f32_16x16x32_bf16 v[82:85], v[238:241], v[234:237], v[82:85]
	ds_read_b128 v[238:241], v233
	ds_read_b128 v[142:145], v200 offset:6144
	s_waitcnt lgkmcnt(7)
	v_mfma_f32_16x16x32_bf16 v[86:89], v[242:245], v[212:215], v[86:89]
	v_mfma_f32_16x16x32_bf16 v[90:93], v[242:245], v[216:219], v[90:93]
	v_mfma_f32_16x16x32_bf16 v[94:97], v[242:245], v[220:223], v[94:97]
	v_mfma_f32_16x16x32_bf16 v[98:101], v[242:245], v[234:237], v[98:101]
	ds_read_b128 v[242:245], v233 offset:2048
	s_waitcnt lgkmcnt(6)
	v_mfma_f32_16x16x32_bf16 v[102:105], v[246:249], v[212:215], v[102:105]
	v_mfma_f32_16x16x32_bf16 v[106:109], v[246:249], v[216:219], v[106:109]
	v_mfma_f32_16x16x32_bf16 v[110:113], v[246:249], v[220:223], v[110:113]
	v_mfma_f32_16x16x32_bf16 v[114:117], v[246:249], v[234:237], v[114:117]
	ds_read_b128 v[246:249], v233 offset:4096
	s_waitcnt lgkmcnt(5)
	v_mfma_f32_16x16x32_bf16 v[118:121], v[250:253], v[212:215], v[118:121]
	v_mfma_f32_16x16x32_bf16 v[122:125], v[250:253], v[216:219], v[122:125]
	v_mfma_f32_16x16x32_bf16 v[126:129], v[250:253], v[220:223], v[126:129]
	v_mfma_f32_16x16x32_bf16 v[2:5], v[250:253], v[234:237], v[2:5]
	ds_read_b128 v[250:253], v233 offset:6144
	s_waitcnt lgkmcnt(3)
	v_mfma_f32_16x16x32_bf16 v[6:9], v[238:241], v[130:133], v[6:9]
	v_mfma_f32_16x16x32_bf16 v[10:13], v[238:241], v[134:137], v[10:13]
	v_mfma_f32_16x16x32_bf16 v[14:17], v[238:241], v[138:141], v[14:17]
	v_mfma_f32_16x16x32_bf16 v[18:21], v[238:241], v[142:145], v[18:21]
	ds_read_b128 v[238:241], v233 offset:8192
	s_waitcnt lgkmcnt(3)
	v_mfma_f32_16x16x32_bf16 v[22:25], v[242:245], v[130:133], v[22:25]
	v_mfma_f32_16x16x32_bf16 v[26:29], v[242:245], v[134:137], v[26:29]
	v_mfma_f32_16x16x32_bf16 v[30:33], v[242:245], v[138:141], v[30:33]
	v_mfma_f32_16x16x32_bf16 v[34:37], v[242:245], v[142:145], v[34:37]
	ds_read_b128 v[242:245], v233 offset:10240
	s_waitcnt lgkmcnt(3)
	v_mfma_f32_16x16x32_bf16 v[38:41], v[246:249], v[130:133], v[38:41]
	v_mfma_f32_16x16x32_bf16 v[42:45], v[246:249], v[134:137], v[42:45]
	v_mfma_f32_16x16x32_bf16 v[46:49], v[246:249], v[138:141], v[46:49]
	v_mfma_f32_16x16x32_bf16 v[50:53], v[246:249], v[142:145], v[50:53]
	ds_read_b128 v[246:249], v233 offset:12288
	s_waitcnt lgkmcnt(3)
	v_mfma_f32_16x16x32_bf16 v[54:57], v[250:253], v[130:133], v[54:57]
	v_mfma_f32_16x16x32_bf16 v[58:61], v[250:253], v[134:137], v[58:61]
	v_mfma_f32_16x16x32_bf16 v[62:65], v[250:253], v[138:141], v[62:65]
	v_mfma_f32_16x16x32_bf16 v[66:69], v[250:253], v[142:145], v[66:69]
	ds_read_b128 v[250:253], v233 offset:14336
	s_waitcnt lgkmcnt(3)
	v_mfma_f32_16x16x32_bf16 v[70:73], v[238:241], v[130:133], v[70:73]
	v_mfma_f32_16x16x32_bf16 v[74:77], v[238:241], v[134:137], v[74:77]
	v_mfma_f32_16x16x32_bf16 v[78:81], v[238:241], v[138:141], v[78:81]
	v_mfma_f32_16x16x32_bf16 v[82:85], v[238:241], v[142:145], v[82:85]
	s_waitcnt lgkmcnt(2)
	v_mfma_f32_16x16x32_bf16 v[86:89], v[242:245], v[130:133], v[86:89]
	v_mfma_f32_16x16x32_bf16 v[90:93], v[242:245], v[134:137], v[90:93]
	v_mfma_f32_16x16x32_bf16 v[94:97], v[242:245], v[138:141], v[94:97]
	v_mfma_f32_16x16x32_bf16 v[98:101], v[242:245], v[142:145], v[98:101]
	s_waitcnt lgkmcnt(0)
	s_waitcnt vmcnt(0)
	s_barrier
; template <int EPI>
; DI void gemm_phase(const P& p, int l, const u16* __restrict__ A, const u16* __restrict__ Bt, int mpx, char* lds) {
;     ...
;     const int cb = n0 + wn * 64;
;     const bool isctx = m0 >= MLAT;
;     const int b = isctx ? ((m0 - MLAT) >> 8) : (m0 >> 11);
;     const int tokw = (isctx ? 2048 + ((m0 - MLAT) & 255) : (m0 & 2047)) + wm * 128;
;     u16* Tl = (u16*)(lds + 65536) + w * (64 * 72);
;     int kind = 0;
;     int tr = 0;
;     bool donorm = false;
;     if (cb >= 2816) { kind = 2; tr = 1; }
;     else if (cb < 256) tr = 1;
;     else if (cb < 512) tr = 0;
;     else if (cb < 1024) tr = 2;
;     else if (cb < 1408) { tr = 3; donorm = true; }
;     else if (cb < 1536) kind = 1;
;     else if (cb < 2048) tr = isctx ? 0 : 4;
;     else if (cb < 2304) kind = 1;
;     else if (cb < 2688) tr = isctx ? 0 : 3;
;     else kind = 1;
	v_mfma_f32_16x16x32_bf16 v[102:105], v[246:249], v[130:133], v[102:105]
	v_mfma_f32_16x16x32_bf16 v[106:109], v[246:249], v[134:137], v[106:109]
	v_mfma_f32_16x16x32_bf16 v[110:113], v[246:249], v[138:141], v[110:113]
	v_mfma_f32_16x16x32_bf16 v[114:117], v[246:249], v[142:145], v[114:117]
	v_mfma_f32_16x16x32_bf16 v[118:121], v[250:253], v[130:133], v[118:121]
	v_mfma_f32_16x16x32_bf16 v[122:125], v[250:253], v[134:137], v[122:125]
	v_mfma_f32_16x16x32_bf16 v[126:129], v[250:253], v[138:141], v[126:129]
	v_mfma_f32_16x16x32_bf16 v[2:5], v[250:253], v[142:145], v[2:5]
	s_nop 0
	v_readfirstlane_b32 s40, v195
	s_lshr_b32 s40, s40, 6
	s_and_b32 s41, s40, 3
	s_lshr_b32 s42, s40, 2
	s_lshr_b32 s43, s46, 6
	s_add_i32 s43, s43, s41
	s_cmp_ge_u32 s66, 0x8000
	s_cselect_b32 s67, 1, 0
	s_mov_b32 s44, 0xffff
	s_mov_b32 s45, 0
	s_bitcmp1_b64 s[44:45], s43
	s_cbranch_scc1 .Lfe_kind0
	s_mov_b32 s44, 0xc00000
	s_mov_b32 s45, 0xc0f
	s_bitcmp1_b64 s[44:45], s43
	s_cbranch_scc1 .Lfe_kind1
	s_cmp_ge_u32 s43, 44
	s_cbranch_scc1 .Lfe_kind2
	s_branch .Lfe_kind0
